# sc0 on LDS-DMA loads (workgroup-scope policy, skips L1 allocation) on top of k-snake + scalar-base addressing
# baseline (speedup 1.0000x reference)
.LBB0_160:
	s_or_b64 exec, exec, s[0:1]
	v_readlane_b32 s26, v241, 6
	s_cmp_eq_u32 s19, 0
	v_mov_b32_e32 v14, v156
	v_readlane_b32 s27, v241, 7
	s_cselect_b64 s[0:1], -1, 0
	s_waitcnt lgkmcnt(0)
	s_barrier
	s_and_b64 vcc, exec, s[26:27]
	v_readfirstlane_b32 s28, v14
	s_cbranch_vccz .LBB0_176
	v_lshlrev_b32_e32 v1, 4, v14
	v_add_u32_e32 v0, 0x2000, v1
	v_ashrrev_i32_e32 v3, 31, v0
	v_lshrrev_b32_e32 v3, 22, v3
	v_add_u32_e32 v3, v0, v3
	v_ashrrev_i32_e32 v8, 10, v3
	v_mul_i32_i24_e32 v3, 0x400, v8
	v_sub_u32_e32 v0, v0, v3
	v_lshrrev_b32_e32 v3, 4, v0
	v_bitop3_b32 v0, v3, v0, 32 bitop3:0x6c
	s_ashr_i32 s29, s28, 6
	v_ashrrev_i32_e32 v3, 31, v0
	s_ashr_i32 s36, s28, 8
	s_lshl_b32 s19, s29, 10
	v_lshrrev_b32_e32 v3, 26, v3
	s_and_b64 s[26:27], s[0:1], exec
	v_add_u32_e32 v3, v0, v3
	v_lshlrev_b32_e32 v4, 3, v8
	s_cselect_b32 s26, 0, 0x5800000
	v_ashrrev_i32_e32 v9, 6, v3
	v_and_b32_e32 v4, -16, v4
	s_add_u32 s33, s88, s26
	v_readlane_b32 s26, v240, 13
	v_add_u32_e32 v4, v9, v4
	s_addc_u32 s56, s26, 0
	v_and_b32_e32 v5, 3, v9
	s_mov_b32 s26, 0x1ffffe0
	v_lshrrev_b32_e32 v6, 2, v4
	v_lshlrev_b32_e32 v7, 1, v4
	v_and_b32_e32 v3, 0xc0, v3
	v_and_or_b32 v5, v4, s26, v5
	v_and_b32_e32 v6, 4, v6
	v_and_b32_e32 v7, 24, v7
	v_sub_u32_e32 v0, v0, v3
	v_or3_b32 v5, v5, v6, v7
	v_lshlrev_b32_e32 v6, 5, v8
	v_ashrrev_i16_sdwa v0, v220, sext(v0) dst_sel:DWORD dst_unused:UNUSED_PAD src0_sel:DWORD src1_sel:BYTE_0
	v_and_b32_e32 v6, 32, v6
	v_bfe_i32 v10, v0, 0, 16
	v_add_lshl_u32 v3, v6, v10, 1
	v_lshl_add_u32 v0, v5, 7, v3
	v_lshl_add_u32 v132, v4, 12, v3
	v_bfe_i32 v3, v14, 27, 1
	v_lshrrev_b32_e32 v3, 22, v3
	v_add_u32_e32 v3, v1, v3
	v_and_b32_e32 v3, 0xfffffc00, v3
	v_sub_u32_e32 v1, v1, v3
	v_lshrrev_b32_e32 v3, 4, v1
	v_ashrrev_i32_e32 v4, 31, v14
	v_bitop3_b32 v1, v3, v1, 32 bitop3:0x6c
	v_lshrrev_b32_e32 v4, 26, v4
	v_ashrrev_i32_e32 v3, 31, v1
	v_add_u32_e32 v4, v14, v4
	v_lshrrev_b32_e32 v3, 26, v3
	v_ashrrev_i32_e32 v12, 6, v4
	v_add_u32_e32 v3, v1, v3
	v_lshlrev_b32_e32 v4, 3, v12
	v_ashrrev_i32_e32 v11, 6, v3
	v_and_b32_e32 v4, -16, v4
	v_add_u32_e32 v4, v11, v4
	v_and_b32_e32 v5, 3, v11
	v_lshrrev_b32_e32 v6, 2, v4
	v_lshlrev_b32_e32 v7, 1, v4
	v_and_b32_e32 v3, 0xc0, v3
	v_and_or_b32 v5, v4, s26, v5
	v_and_b32_e32 v6, 4, v6
	v_and_b32_e32 v7, 24, v7
	v_sub_u32_e32 v1, v1, v3
	v_or3_b32 v5, v5, v6, v7
	v_lshlrev_b32_e32 v6, 5, v12
	v_ashrrev_i16_sdwa v1, v220, sext(v1) dst_sel:DWORD dst_unused:UNUSED_PAD src0_sel:DWORD src1_sel:BYTE_0
	v_readlane_b32 s26, v241, 51
	v_and_b32_e32 v6, 32, v6
	v_bfe_i32 v13, v1, 0, 16
	v_readlane_b32 s27, v241, 52
	s_add_u32 s34, s33, s26
	v_add_lshl_u32 v1, v6, v13, 1
	s_addc_u32 s35, s56, s27
	s_add_i32 s57, s19, 0
	v_lshl_add_u32 v134, v5, 7, v1
	s_add_i32 m0, s57, 0x10000
	v_lshl_add_u32 v136, v4, 12, v1
	global_load_lds_dwordx4 v134, s[34:35] sc0
	s_add_i32 m0, s57, 0x12000
	s_add_u32 s26, s34, 0x4000
	global_load_lds_dwordx4 v0, s[34:35] sc0
	s_addc_u32 s27, s35, 0
	s_add_i32 m0, s57, 0x14000
	v_mov_b32_e32 v137, v2
	global_load_lds_dwordx4 v134, s[26:27] sc0
	s_add_i32 m0, s57, 0x16000
	v_mov_b32_e32 v133, v2
	global_load_lds_dwordx4 v0, s[26:27] sc0
	v_readlane_b32 s26, v241, 62
	v_readlane_b32 s27, v241, 63
	s_add_u32 s50, s20, s26
	s_addc_u32 s51, s21, s27
	s_add_i32 s58, s57, 0x2000
	s_mov_b32 m0, s57
	s_add_u32 s26, s50, 0x80000
	global_load_lds_dwordx4 v136, s[50:51] sc0
	s_mov_b32 m0, s58
	s_addc_u32 s27, s51, 0
	s_add_i32 s59, s57, 0x4000
	global_load_lds_dwordx4 v132, s[50:51] sc0
	s_mov_b32 m0, s59
	s_add_i32 s60, s57, 0x6000
	global_load_lds_dwordx4 v136, s[26:27] sc0
	s_mov_b32 m0, s60
	s_cmp_eq_u32 s36, 1
	global_load_lds_dwordx4 v132, s[26:27] sc0
	v_lshl_add_u64 v[4:5], s[50:51], 0, v[136:137]
	s_cselect_b64 s[26:27], -1, 0
	s_cmp_lg_u32 s36, 1
	v_lshl_add_u64 v[6:7], s[50:51], 0, v[132:133]
	s_cbranch_scc1 .LBB0_163
	s_barrier

.LBB0_169:
	s_add_u32 s34, s50, 0xfff80080
	s_addc_u32 s35, s51, -1
	s_add_i32 s52, 0, 0x10000
	s_cmp_eq_u32 s77, 28
	s_cselect_b32 s55, s36, s35
	s_cselect_b32 s54, s37, s34
	v_add_u32_e32 v145, s52, v142
	s_cselect_b32 s35, s41, s76
	s_cselect_b32 s34, s43, s71
	s_add_i32 s53, 0, 0x14000
	ds_read_b128 v[146:149], v145
	ds_read_b128 v[150:153], v145 offset:1024
	ds_read_b128 v[172:175], v145 offset:2048
	ds_read_b128 v[176:179], v145 offset:3072
	v_add_u32_e32 v145, s53, v142
	ds_read_b128 v[180:183], v145
	ds_read_b128 v[184:187], v145 offset:1024
	ds_read_b128 v[188:191], v145 offset:2048
	ds_read_b128 v[192:195], v145 offset:3072
	s_add_i32 m0, s57, 0xc000
	ds_read_b128 v[196:199], v144
	ds_read_b128 v[200:203], v144 offset:1024
	ds_read_b128 v[204:207], v144 offset:2048
	ds_read_b128 v[208:211], v144 offset:3072
	ds_read_b128 v[212:215], v144 offset:4096
	ds_read_b128 v[216:219], v144 offset:5120
	ds_read_b128 v[228:231], v144 offset:6144
	ds_read_b128 v[232:235], v144 offset:7168
	global_load_lds_dwordx4 v138, s[50:51] sc0
	s_add_i32 m0, s57, 0xe000
	s_nop 0
	global_load_lds_dwordx4 v140, s[50:51] sc0
	s_waitcnt vmcnt(8)
	s_waitcnt lgkmcnt(0)
	s_barrier
	s_setprio 1
	v_mfma_f32_16x16x32_bf16 v[128:131], v[146:149], v[196:199], v[128:131]
	v_mfma_f32_16x16x32_bf16 v[128:131], v[150:153], v[200:203], v[128:131]
	v_mfma_f32_16x16x32_bf16 v[124:127], v[176:179], v[200:203], v[124:127]
	v_mfma_f32_16x16x32_bf16 v[124:127], v[172:175], v[196:199], v[124:127]
	v_mfma_f32_16x16x32_bf16 v[108:111], v[172:175], v[204:207], v[108:111]
	v_mfma_f32_16x16x32_bf16 v[108:111], v[176:179], v[208:211], v[108:111]
	v_mfma_f32_16x16x32_bf16 v[112:115], v[150:153], v[208:211], v[112:115]
	v_mfma_f32_16x16x32_bf16 v[112:115], v[146:149], v[204:207], v[112:115]
	v_mfma_f32_16x16x32_bf16 v[96:99], v[146:149], v[212:215], v[96:99]
	v_mfma_f32_16x16x32_bf16 v[96:99], v[150:153], v[216:219], v[96:99]
	v_mfma_f32_16x16x32_bf16 v[92:95], v[176:179], v[216:219], v[92:95]
	v_mfma_f32_16x16x32_bf16 v[92:95], v[172:175], v[212:215], v[92:95]
	v_mfma_f32_16x16x32_bf16 v[76:79], v[172:175], v[228:231], v[76:79]
	v_mfma_f32_16x16x32_bf16 v[76:79], v[176:179], v[232:235], v[76:79]
	v_mfma_f32_16x16x32_bf16 v[80:83], v[150:153], v[232:235], v[80:83]
	v_mfma_f32_16x16x32_bf16 v[80:83], v[146:149], v[228:231], v[80:83]
	v_mfma_f32_16x16x32_bf16 v[120:123], v[180:183], v[196:199], v[120:123]
	v_mfma_f32_16x16x32_bf16 v[120:123], v[184:187], v[200:203], v[120:123]
	v_mfma_f32_16x16x32_bf16 v[116:119], v[192:195], v[200:203], v[116:119]
	v_mfma_f32_16x16x32_bf16 v[116:119], v[188:191], v[196:199], v[116:119]
	v_mfma_f32_16x16x32_bf16 v[100:103], v[188:191], v[204:207], v[100:103]
	v_mfma_f32_16x16x32_bf16 v[100:103], v[192:195], v[208:211], v[100:103]
	v_mfma_f32_16x16x32_bf16 v[104:107], v[184:187], v[208:211], v[104:107]
	v_mfma_f32_16x16x32_bf16 v[104:107], v[180:183], v[204:207], v[104:107]
	v_mfma_f32_16x16x32_bf16 v[88:91], v[180:183], v[212:215], v[88:91]
	v_mfma_f32_16x16x32_bf16 v[88:91], v[184:187], v[216:219], v[88:91]
	v_mfma_f32_16x16x32_bf16 v[84:87], v[192:195], v[216:219], v[84:87]
	v_mfma_f32_16x16x32_bf16 v[84:87], v[188:191], v[212:215], v[84:87]
	v_mfma_f32_16x16x32_bf16 v[68:71], v[188:191], v[228:231], v[68:71]
	v_mfma_f32_16x16x32_bf16 v[68:71], v[192:195], v[232:235], v[68:71]
	v_mfma_f32_16x16x32_bf16 v[72:75], v[184:187], v[232:235], v[72:75]
	v_mfma_f32_16x16x32_bf16 v[72:75], v[180:183], v[228:231], v[72:75]
	s_setprio 0
	s_barrier
	s_add_u32 s100, s54, s14
	s_addc_u32 s101, s55, s15
	s_add_i32 s52, s52, s19
	s_mov_b32 m0, s52
	ds_read_b128 v[196:199], v144 offset:16384
	ds_read_b128 v[200:203], v144 offset:17408
	ds_read_b128 v[204:207], v144 offset:18432
	ds_read_b128 v[208:211], v144 offset:19456
	ds_read_b128 v[212:215], v144 offset:20480
	ds_read_b128 v[216:219], v144 offset:21504
	ds_read_b128 v[228:231], v144 offset:22528
	ds_read_b128 v[232:235], v144 offset:23552
	global_load_lds_dwordx4 v134, s[34:35] sc0
	s_add_i32 m0, s52, 0x2000
	s_add_u32 s96, s34, 0x4000
	s_addc_u32 s97, s35, 0
	s_add_i32 s52, s53, s19
	global_load_lds_dwordx4 v0, s[34:35] sc0
	s_mov_b32 m0, s52
	s_nop 0
	global_load_lds_dwordx4 v134, s[96:97] sc0
	s_add_i32 m0, s52, 0x2000
	s_nop 0
	global_load_lds_dwordx4 v0, s[96:97] sc0
	s_mov_b32 m0, s57
	s_nop 0
	global_load_lds_dwordx4 v136, s[54:55] sc0
	s_mov_b32 m0, s58
	s_nop 0
	global_load_lds_dwordx4 v132, s[54:55] sc0
	s_waitcnt vmcnt(8)
	s_waitcnt lgkmcnt(0)
	s_barrier
	s_setprio 1
	v_mfma_f32_16x16x32_bf16 v[64:67], v[146:149], v[196:199], v[64:67]
	v_mfma_f32_16x16x32_bf16 v[64:67], v[150:153], v[200:203], v[64:67]
	v_mfma_f32_16x16x32_bf16 v[60:63], v[176:179], v[200:203], v[60:63]
	v_mfma_f32_16x16x32_bf16 v[60:63], v[172:175], v[196:199], v[60:63]
	v_mfma_f32_16x16x32_bf16 v[44:47], v[172:175], v[204:207], v[44:47]
	v_mfma_f32_16x16x32_bf16 v[44:47], v[176:179], v[208:211], v[44:47]
	v_mfma_f32_16x16x32_bf16 v[48:51], v[150:153], v[208:211], v[48:51]
	v_mfma_f32_16x16x32_bf16 v[48:51], v[146:149], v[204:207], v[48:51]
	v_mfma_f32_16x16x32_bf16 v[32:35], v[146:149], v[212:215], v[32:35]
	v_mfma_f32_16x16x32_bf16 v[32:35], v[150:153], v[216:219], v[32:35]
	v_mfma_f32_16x16x32_bf16 v[28:31], v[176:179], v[216:219], v[28:31]
	v_mfma_f32_16x16x32_bf16 v[28:31], v[172:175], v[212:215], v[28:31]
	v_mfma_f32_16x16x32_bf16 v[12:15], v[172:175], v[228:231], v[12:15]
	v_mfma_f32_16x16x32_bf16 v[12:15], v[176:179], v[232:235], v[12:15]
	v_mfma_f32_16x16x32_bf16 v[16:19], v[150:153], v[232:235], v[16:19]
	v_mfma_f32_16x16x32_bf16 v[16:19], v[146:149], v[228:231], v[16:19]
	v_mfma_f32_16x16x32_bf16 v[56:59], v[180:183], v[196:199], v[56:59]
	v_mfma_f32_16x16x32_bf16 v[56:59], v[184:187], v[200:203], v[56:59]
	v_mfma_f32_16x16x32_bf16 v[52:55], v[192:195], v[200:203], v[52:55]
	v_mfma_f32_16x16x32_bf16 v[52:55], v[188:191], v[196:199], v[52:55]
	v_mfma_f32_16x16x32_bf16 v[36:39], v[188:191], v[204:207], v[36:39]
	v_mfma_f32_16x16x32_bf16 v[36:39], v[192:195], v[208:211], v[36:39]
	v_mfma_f32_16x16x32_bf16 v[40:43], v[184:187], v[208:211], v[40:43]
	v_mfma_f32_16x16x32_bf16 v[40:43], v[180:183], v[204:207], v[40:43]
	v_mfma_f32_16x16x32_bf16 v[24:27], v[180:183], v[212:215], v[24:27]
	v_mfma_f32_16x16x32_bf16 v[24:27], v[184:187], v[216:219], v[24:27]
	v_mfma_f32_16x16x32_bf16 v[20:23], v[192:195], v[216:219], v[20:23]
	v_mfma_f32_16x16x32_bf16 v[20:23], v[188:191], v[212:215], v[20:23]
	v_mfma_f32_16x16x32_bf16 v[4:7], v[188:191], v[228:231], v[4:7]
	v_mfma_f32_16x16x32_bf16 v[4:7], v[192:195], v[232:235], v[4:7]
	v_mfma_f32_16x16x32_bf16 v[8:11], v[184:187], v[232:235], v[8:11]
	v_mfma_f32_16x16x32_bf16 v[8:11], v[180:183], v[228:231], v[8:11]
	s_setprio 0
	s_barrier
	s_add_i32 s52, 0, 0x18000
	v_add_u32_e32 v145, s52, v142
	s_add_i32 s53, 0, 0x1c000
	ds_read_b128 v[146:149], v145
	ds_read_b128 v[150:153], v145 offset:1024
	ds_read_b128 v[172:175], v145 offset:2048
	ds_read_b128 v[176:179], v145 offset:3072
	v_add_u32_e32 v145, s53, v142
	ds_read_b128 v[180:183], v145
	ds_read_b128 v[184:187], v145 offset:1024
	ds_read_b128 v[188:191], v145 offset:2048
	ds_read_b128 v[192:195], v145 offset:3072
	s_add_u32 s54, s54, 0x80000
	s_addc_u32 s55, s55, 0
	s_mov_b32 m0, s59
	ds_read_b128 v[196:199], v144 offset:32768
	ds_read_b128 v[200:203], v144 offset:33792
	ds_read_b128 v[204:207], v144 offset:34816
	ds_read_b128 v[208:211], v144 offset:35840
	ds_read_b128 v[212:215], v144 offset:36864
	ds_read_b128 v[216:219], v144 offset:37888
	ds_read_b128 v[228:231], v144 offset:38912
	ds_read_b128 v[232:235], v144 offset:39936
	global_load_lds_dwordx4 v136, s[54:55] sc0
	s_mov_b32 m0, s60
	s_nop 0
	global_load_lds_dwordx4 v132, s[54:55] sc0
	s_waitcnt vmcnt(8)
	s_waitcnt lgkmcnt(0)
	s_barrier
	s_setprio 1
	v_mfma_f32_16x16x32_bf16 v[128:131], v[146:149], v[196:199], v[128:131]
	v_mfma_f32_16x16x32_bf16 v[128:131], v[150:153], v[200:203], v[128:131]
	v_mfma_f32_16x16x32_bf16 v[124:127], v[176:179], v[200:203], v[124:127]
	v_mfma_f32_16x16x32_bf16 v[124:127], v[172:175], v[196:199], v[124:127]
	v_mfma_f32_16x16x32_bf16 v[108:111], v[172:175], v[204:207], v[108:111]
	v_mfma_f32_16x16x32_bf16 v[108:111], v[176:179], v[208:211], v[108:111]
	v_mfma_f32_16x16x32_bf16 v[112:115], v[150:153], v[208:211], v[112:115]
	v_mfma_f32_16x16x32_bf16 v[112:115], v[146:149], v[204:207], v[112:115]
	v_mfma_f32_16x16x32_bf16 v[96:99], v[146:149], v[212:215], v[96:99]
	v_mfma_f32_16x16x32_bf16 v[96:99], v[150:153], v[216:219], v[96:99]
	v_mfma_f32_16x16x32_bf16 v[92:95], v[176:179], v[216:219], v[92:95]
	v_mfma_f32_16x16x32_bf16 v[92:95], v[172:175], v[212:215], v[92:95]
	v_mfma_f32_16x16x32_bf16 v[76:79], v[172:175], v[228:231], v[76:79]
	v_mfma_f32_16x16x32_bf16 v[76:79], v[176:179], v[232:235], v[76:79]
	v_mfma_f32_16x16x32_bf16 v[80:83], v[150:153], v[232:235], v[80:83]
	v_mfma_f32_16x16x32_bf16 v[80:83], v[146:149], v[228:231], v[80:83]
	v_mfma_f32_16x16x32_bf16 v[120:123], v[180:183], v[196:199], v[120:123]
	v_mfma_f32_16x16x32_bf16 v[120:123], v[184:187], v[200:203], v[120:123]
	v_mfma_f32_16x16x32_bf16 v[116:119], v[192:195], v[200:203], v[116:119]
	v_mfma_f32_16x16x32_bf16 v[116:119], v[188:191], v[196:199], v[116:119]
	v_mfma_f32_16x16x32_bf16 v[100:103], v[188:191], v[204:207], v[100:103]
	v_mfma_f32_16x16x32_bf16 v[100:103], v[192:195], v[208:211], v[100:103]
	v_mfma_f32_16x16x32_bf16 v[104:107], v[184:187], v[208:211], v[104:107]
	v_mfma_f32_16x16x32_bf16 v[104:107], v[180:183], v[204:207], v[104:107]
	v_mfma_f32_16x16x32_bf16 v[88:91], v[180:183], v[212:215], v[88:91]
	v_mfma_f32_16x16x32_bf16 v[88:91], v[184:187], v[216:219], v[88:91]
	v_mfma_f32_16x16x32_bf16 v[84:87], v[192:195], v[216:219], v[84:87]
	v_mfma_f32_16x16x32_bf16 v[84:87], v[188:191], v[212:215], v[84:87]
	v_mfma_f32_16x16x32_bf16 v[68:71], v[188:191], v[228:231], v[68:71]
	v_mfma_f32_16x16x32_bf16 v[68:71], v[192:195], v[232:235], v[68:71]
	v_mfma_f32_16x16x32_bf16 v[72:75], v[184:187], v[232:235], v[72:75]
	v_mfma_f32_16x16x32_bf16 v[72:75], v[180:183], v[228:231], v[72:75]
	s_setprio 0
	s_barrier
	s_add_u32 s54, s34, 0x160000
	s_addc_u32 s55, s35, 0
	s_add_i32 s52, s52, s19
	s_mov_b32 m0, s52
	ds_read_b128 v[196:199], v144 offset:49152
	ds_read_b128 v[200:203], v144 offset:50176
	ds_read_b128 v[204:207], v144 offset:51200
	ds_read_b128 v[208:211], v144 offset:52224
	ds_read_b128 v[212:215], v144 offset:53248
	ds_read_b128 v[216:219], v144 offset:54272
	ds_read_b128 v[228:231], v144 offset:55296
	ds_read_b128 v[232:235], v144 offset:56320
	global_load_lds_dwordx4 v134, s[54:55] sc0
	s_add_i32 m0, s52, 0x2000
	s_add_u32 s34, s34, 0x164000
	s_addc_u32 s35, s35, 0
	s_add_i32 s52, s53, s19
	global_load_lds_dwordx4 v0, s[54:55] sc0
	s_mov_b32 m0, s52
	s_nop 0
	global_load_lds_dwordx4 v134, s[34:35] sc0
	s_add_i32 m0, s52, 0x2000
	s_nop 0
	global_load_lds_dwordx4 v0, s[34:35] sc0
	s_mov_b32 m0, s61
	s_nop 0
	global_load_lds_dwordx4 v136, s[100:101] sc0
	s_mov_b32 m0, s62
	s_nop 0
	global_load_lds_dwordx4 v132, s[100:101] sc0
	s_waitcnt vmcnt(8)
	s_waitcnt lgkmcnt(0)
	s_barrier
	s_setprio 1
	v_mfma_f32_16x16x32_bf16 v[64:67], v[146:149], v[196:199], v[64:67]
	v_mfma_f32_16x16x32_bf16 v[64:67], v[150:153], v[200:203], v[64:67]
	v_mfma_f32_16x16x32_bf16 v[60:63], v[176:179], v[200:203], v[60:63]
	v_mfma_f32_16x16x32_bf16 v[60:63], v[172:175], v[196:199], v[60:63]
	v_mfma_f32_16x16x32_bf16 v[44:47], v[172:175], v[204:207], v[44:47]
	v_mfma_f32_16x16x32_bf16 v[44:47], v[176:179], v[208:211], v[44:47]
	v_mfma_f32_16x16x32_bf16 v[48:51], v[150:153], v[208:211], v[48:51]
	v_mfma_f32_16x16x32_bf16 v[48:51], v[146:149], v[204:207], v[48:51]
	v_mfma_f32_16x16x32_bf16 v[32:35], v[146:149], v[212:215], v[32:35]
	v_mfma_f32_16x16x32_bf16 v[32:35], v[150:153], v[216:219], v[32:35]
	v_mfma_f32_16x16x32_bf16 v[28:31], v[176:179], v[216:219], v[28:31]
	v_mfma_f32_16x16x32_bf16 v[28:31], v[172:175], v[212:215], v[28:31]
	v_mfma_f32_16x16x32_bf16 v[12:15], v[172:175], v[228:231], v[12:15]
	v_mfma_f32_16x16x32_bf16 v[12:15], v[176:179], v[232:235], v[12:15]
	v_mfma_f32_16x16x32_bf16 v[16:19], v[150:153], v[232:235], v[16:19]
	v_mfma_f32_16x16x32_bf16 v[16:19], v[146:149], v[228:231], v[16:19]
	v_mfma_f32_16x16x32_bf16 v[56:59], v[180:183], v[196:199], v[56:59]
	v_mfma_f32_16x16x32_bf16 v[56:59], v[184:187], v[200:203], v[56:59]
	v_mfma_f32_16x16x32_bf16 v[52:55], v[192:195], v[200:203], v[52:55]
	v_mfma_f32_16x16x32_bf16 v[52:55], v[188:191], v[196:199], v[52:55]
	v_mfma_f32_16x16x32_bf16 v[36:39], v[188:191], v[204:207], v[36:39]
	v_mfma_f32_16x16x32_bf16 v[36:39], v[192:195], v[208:211], v[36:39]
	v_mfma_f32_16x16x32_bf16 v[40:43], v[184:187], v[208:211], v[40:43]
	v_mfma_f32_16x16x32_bf16 v[40:43], v[180:183], v[204:207], v[40:43]
	v_mfma_f32_16x16x32_bf16 v[24:27], v[180:183], v[212:215], v[24:27]
	v_mfma_f32_16x16x32_bf16 v[24:27], v[184:187], v[216:219], v[24:27]
	v_mfma_f32_16x16x32_bf16 v[20:23], v[192:195], v[216:219], v[20:23]
	v_mfma_f32_16x16x32_bf16 v[20:23], v[188:191], v[212:215], v[20:23]
	v_mfma_f32_16x16x32_bf16 v[4:7], v[188:191], v[228:231], v[4:7]
	v_mfma_f32_16x16x32_bf16 v[4:7], v[192:195], v[232:235], v[4:7]
	v_mfma_f32_16x16x32_bf16 v[8:11], v[184:187], v[232:235], v[8:11]
	v_mfma_f32_16x16x32_bf16 v[8:11], v[180:183], v[228:231], v[8:11]
	s_setprio 0
	s_barrier
	s_add_i32 s77, s77, 2
	s_add_u32 s71, s71, 0x2c0000
	s_addc_u32 s76, s76, 0
	s_add_u32 s50, s50, 0x100
	s_addc_u32 s51, s51, 0
	s_cmp_gt_u32 s77, 29
	s_cbranch_scc0 .LBB0_169
	s_and_b64 vcc, exec, s[28:29]
	s_cbranch_vccz .LBB0_172
	s_barrier

.LBB0_234:
	s_or_b64 exec, exec, s[0:1]
	v_mov_b32_e32 v14, v156
	s_waitcnt lgkmcnt(0)
	s_barrier
	s_and_b64 vcc, exec, s[38:39]
	v_readfirstlane_b32 s36, v14
	v_writelane_b32 v240, s88, 15
	s_cbranch_vccnz .LBB0_347
	v_lshlrev_b32_e32 v1, 4, v14
	v_add_u32_e32 v0, 0x2000, v1
	v_ashrrev_i32_e32 v3, 31, v0
	v_lshrrev_b32_e32 v3, 22, v3
	v_add_u32_e32 v3, v0, v3
	v_ashrrev_i32_e32 v8, 10, v3
	v_mul_i32_i24_e32 v3, 0x400, v8
	v_sub_u32_e32 v0, v0, v3
	v_lshrrev_b32_e32 v3, 4, v0
	v_bitop3_b32 v0, v3, v0, 32 bitop3:0x6c
	v_ashrrev_i32_e32 v3, 31, v0
	v_lshrrev_b32_e32 v3, 26, v3
	s_ashr_i32 s27, s36, 6
	v_add_u32_e32 v3, v0, v3
	v_lshlrev_b32_e32 v4, 3, v8
	s_ashr_i32 s26, s36, 8
	s_lshl_b32 s2, s27, 10
	v_ashrrev_i32_e32 v9, 6, v3
	v_and_b32_e32 v4, -16, v4
	s_add_u32 s19, s88, 0x4200000
	v_readlane_b32 s0, v240, 13
	v_add_u32_e32 v4, v9, v4
	s_addc_u32 s33, s0, 0
	v_and_b32_e32 v5, 3, v9
	s_mov_b32 s0, 0x1ffffe0
	v_lshrrev_b32_e32 v6, 2, v4
	v_lshlrev_b32_e32 v7, 1, v4
	v_and_b32_e32 v3, 0xc0, v3
	v_and_or_b32 v5, v4, s0, v5
	v_and_b32_e32 v6, 4, v6
	v_and_b32_e32 v7, 24, v7
	v_sub_u32_e32 v0, v0, v3
	v_or3_b32 v5, v5, v6, v7
	v_lshlrev_b32_e32 v6, 5, v8
	v_ashrrev_i16_sdwa v0, v220, sext(v0) dst_sel:DWORD dst_unused:UNUSED_PAD src0_sel:DWORD src1_sel:BYTE_0
	v_and_b32_e32 v6, 32, v6
	v_bfe_i32 v10, v0, 0, 16
	v_add_lshl_u32 v3, v6, v10, 1
	v_lshl_add_u32 v0, v5, 7, v3
	v_lshl_add_u32 v148, v4, 12, v3
	v_bfe_i32 v3, v14, 27, 1
	v_lshrrev_b32_e32 v3, 22, v3
	v_add_u32_e32 v3, v1, v3
	v_and_b32_e32 v3, 0xfffffc00, v3
	v_sub_u32_e32 v1, v1, v3
	v_lshrrev_b32_e32 v3, 4, v1
	v_ashrrev_i32_e32 v4, 31, v14
	v_bitop3_b32 v1, v3, v1, 32 bitop3:0x6c
	v_lshrrev_b32_e32 v4, 26, v4
	v_ashrrev_i32_e32 v3, 31, v1
	v_add_u32_e32 v4, v14, v4
	v_lshrrev_b32_e32 v3, 26, v3
	v_ashrrev_i32_e32 v12, 6, v4
	v_add_u32_e32 v3, v1, v3
	v_lshlrev_b32_e32 v4, 3, v12
	v_ashrrev_i32_e32 v11, 6, v3
	v_and_b32_e32 v4, -16, v4
	v_add_u32_e32 v4, v11, v4
	v_and_b32_e32 v5, 3, v11
	v_lshrrev_b32_e32 v6, 2, v4
	v_lshlrev_b32_e32 v7, 1, v4
	v_and_b32_e32 v3, 0xc0, v3
	v_and_or_b32 v5, v4, s0, v5
	v_and_b32_e32 v6, 4, v6
	v_and_b32_e32 v7, 24, v7
	v_sub_u32_e32 v1, v1, v3
	v_or3_b32 v5, v5, v6, v7
	v_lshlrev_b32_e32 v6, 5, v12
	v_ashrrev_i16_sdwa v1, v220, sext(v1) dst_sel:DWORD dst_unused:UNUSED_PAD src0_sel:DWORD src1_sel:BYTE_0
	v_readlane_b32 s0, v241, 55
	v_and_b32_e32 v6, 32, v6
	v_bfe_i32 v13, v1, 0, 16
	v_readlane_b32 s1, v241, 56
	s_add_u32 s34, s19, s0
	v_add_lshl_u32 v1, v6, v13, 1
	s_addc_u32 s35, s33, s1
	s_add_i32 s69, s2, 0
	v_lshl_add_u32 v150, v5, 7, v1
	s_add_i32 m0, s69, 0x10000
	v_lshl_add_u32 v152, v4, 12, v1
	global_load_lds_dwordx4 v150, s[34:35] sc0
	s_add_i32 m0, s69, 0x12000
	s_add_u32 s0, s34, 0x4000
	global_load_lds_dwordx4 v0, s[34:35] sc0
	s_addc_u32 s1, s35, 0
	s_add_i32 m0, s69, 0x14000
	v_mov_b32_e32 v153, v2
	global_load_lds_dwordx4 v150, s[0:1] sc0
	s_add_i32 m0, s69, 0x16000
	v_mov_b32_e32 v149, v2
	global_load_lds_dwordx4 v0, s[0:1] sc0
	v_readlane_b32 s0, v240, 2
	v_readlane_b32 s1, v240, 3
	s_add_u32 s44, s20, s0
	s_addc_u32 s45, s21, s1
	s_add_i32 s71, s69, 0x2000
	s_mov_b32 m0, s69
	s_add_u32 s0, s44, 0x80000
	global_load_lds_dwordx4 v152, s[44:45] sc0
	s_mov_b32 m0, s71
	s_addc_u32 s1, s45, 0
	s_add_i32 s88, s69, 0x4000
	global_load_lds_dwordx4 v148, s[44:45] sc0
	s_mov_b32 m0, s88
	s_add_i32 s96, s69, 0x6000
	global_load_lds_dwordx4 v152, s[0:1] sc0
	s_mov_b32 m0, s96
	s_cmp_eq_u32 s26, 1
	global_load_lds_dwordx4 v148, s[0:1] sc0
	v_lshl_add_u64 v[4:5], s[44:45], 0, v[152:153]
	s_cselect_b64 s[0:1], -1, 0
	s_cmp_lg_u32 s26, 1
	v_lshl_add_u64 v[6:7], s[44:45], 0, v[148:149]
	s_cbranch_scc1 .LBB0_237
	s_barrier

.LBB0_243:
	s_add_u32 s34, s44, 0xfff80080
	s_addc_u32 s35, s45, -1
	s_add_i32 s52, 0, 0x10000
	s_cmp_eq_u32 vcc_hi, 28
	s_cselect_b32 s47, s36, s35
	s_cselect_b32 s46, s37, s34
	s_cselect_b32 s35, s55, vcc_lo
	s_cselect_b32 s34, s57, s63
	s_add_i32 s68, 0, 0x14000
	v_add_u32_e32 v144, s52, v155
	v_add_u32_e32 v180, s68, v155
	ds_read_b128 v[132:135], v144
	ds_read_b128 v[136:139], v144 offset:1024
	ds_read_b128 v[140:143], v144 offset:2048
	ds_read_b128 v[144:147], v144 offset:3072
	ds_read_b128 v[176:179], v180
	ds_read_b128 v[182:185], v180 offset:1024
	ds_read_b128 v[186:189], v180 offset:2048
	ds_read_b128 v[190:193], v180 offset:3072
	s_add_i32 m0, s69, 0xc000
	ds_read_b128 v[194:197], v181
	ds_read_b128 v[198:201], v181 offset:1024
	ds_read_b128 v[202:205], v181 offset:2048
	ds_read_b128 v[206:209], v181 offset:3072
	ds_read_b128 v[210:213], v181 offset:4096
	ds_read_b128 v[214:217], v181 offset:5120
	ds_read_b128 v[228:231], v181 offset:6144
	ds_read_b128 v[232:235], v181 offset:7168
	global_load_lds_dwordx4 v172, s[44:45] sc0
	s_add_i32 m0, s69, 0xe000
	s_nop 0
	global_load_lds_dwordx4 v174, s[44:45] sc0
	s_waitcnt vmcnt(8)
	s_waitcnt lgkmcnt(0)
	s_barrier
	s_setprio 1
	v_mfma_f32_16x16x32_bf16 v[128:131], v[132:135], v[194:197], v[128:131]
	v_mfma_f32_16x16x32_bf16 v[128:131], v[136:139], v[198:201], v[128:131]
	v_mfma_f32_16x16x32_bf16 v[124:127], v[144:147], v[198:201], v[124:127]
	v_mfma_f32_16x16x32_bf16 v[124:127], v[140:143], v[194:197], v[124:127]
	v_mfma_f32_16x16x32_bf16 v[108:111], v[140:143], v[202:205], v[108:111]
	v_mfma_f32_16x16x32_bf16 v[108:111], v[144:147], v[206:209], v[108:111]
	v_mfma_f32_16x16x32_bf16 v[112:115], v[136:139], v[206:209], v[112:115]
	v_mfma_f32_16x16x32_bf16 v[112:115], v[132:135], v[202:205], v[112:115]
	v_mfma_f32_16x16x32_bf16 v[96:99], v[132:135], v[210:213], v[96:99]
	v_mfma_f32_16x16x32_bf16 v[96:99], v[136:139], v[214:217], v[96:99]
	v_mfma_f32_16x16x32_bf16 v[92:95], v[144:147], v[214:217], v[92:95]
	v_mfma_f32_16x16x32_bf16 v[92:95], v[140:143], v[210:213], v[92:95]
	v_mfma_f32_16x16x32_bf16 v[76:79], v[140:143], v[228:231], v[76:79]
	v_mfma_f32_16x16x32_bf16 v[76:79], v[144:147], v[232:235], v[76:79]
	v_mfma_f32_16x16x32_bf16 v[80:83], v[136:139], v[232:235], v[80:83]
	v_mfma_f32_16x16x32_bf16 v[80:83], v[132:135], v[228:231], v[80:83]
	v_mfma_f32_16x16x32_bf16 v[120:123], v[176:179], v[194:197], v[120:123]
	v_mfma_f32_16x16x32_bf16 v[120:123], v[182:185], v[198:201], v[120:123]
	v_mfma_f32_16x16x32_bf16 v[116:119], v[190:193], v[198:201], v[116:119]
	v_mfma_f32_16x16x32_bf16 v[116:119], v[186:189], v[194:197], v[116:119]
	v_mfma_f32_16x16x32_bf16 v[100:103], v[186:189], v[202:205], v[100:103]
	v_mfma_f32_16x16x32_bf16 v[100:103], v[190:193], v[206:209], v[100:103]
	v_mfma_f32_16x16x32_bf16 v[104:107], v[182:185], v[206:209], v[104:107]
	v_mfma_f32_16x16x32_bf16 v[104:107], v[176:179], v[202:205], v[104:107]
	v_mfma_f32_16x16x32_bf16 v[88:91], v[176:179], v[210:213], v[88:91]
	v_mfma_f32_16x16x32_bf16 v[88:91], v[182:185], v[214:217], v[88:91]
	v_mfma_f32_16x16x32_bf16 v[84:87], v[190:193], v[214:217], v[84:87]
	v_mfma_f32_16x16x32_bf16 v[84:87], v[186:189], v[210:213], v[84:87]
	v_mfma_f32_16x16x32_bf16 v[68:71], v[186:189], v[228:231], v[68:71]
	v_mfma_f32_16x16x32_bf16 v[68:71], v[190:193], v[232:235], v[68:71]
	v_mfma_f32_16x16x32_bf16 v[72:75], v[182:185], v[232:235], v[72:75]
	v_mfma_f32_16x16x32_bf16 v[72:75], v[176:179], v[228:231], v[72:75]
	s_setprio 0
	s_barrier
	s_add_u32 s100, s46, s14
	s_addc_u32 s101, s47, s15
	s_add_i32 s52, s52, s2
	s_mov_b32 m0, s52
	ds_read_b128 v[194:197], v181 offset:16384
	ds_read_b128 v[198:201], v181 offset:17408
	ds_read_b128 v[202:205], v181 offset:18432
	ds_read_b128 v[206:209], v181 offset:19456
	ds_read_b128 v[210:213], v181 offset:20480
	ds_read_b128 v[214:217], v181 offset:21504
	ds_read_b128 v[228:231], v181 offset:22528
	ds_read_b128 v[232:235], v181 offset:23552
	global_load_lds_dwordx4 v150, s[34:35] sc0
	s_add_i32 m0, s52, 0x2000
	s_add_u32 s52, s34, 0x4000
	s_addc_u32 s53, s35, 0
	s_add_i32 s68, s68, s2
	global_load_lds_dwordx4 v0, s[34:35] sc0
	s_mov_b32 m0, s68
	s_nop 0
	global_load_lds_dwordx4 v150, s[52:53] sc0
	s_add_i32 m0, s68, 0x2000
	s_nop 0
	global_load_lds_dwordx4 v0, s[52:53] sc0
	s_mov_b32 m0, s69
	s_nop 0
	global_load_lds_dwordx4 v152, s[46:47] sc0
	s_mov_b32 m0, s71
	s_nop 0
	global_load_lds_dwordx4 v148, s[46:47] sc0
	s_waitcnt vmcnt(8)
	s_waitcnt lgkmcnt(0)
	s_barrier
	s_setprio 1
	v_mfma_f32_16x16x32_bf16 v[64:67], v[132:135], v[194:197], v[64:67]
	v_mfma_f32_16x16x32_bf16 v[64:67], v[136:139], v[198:201], v[64:67]
	v_mfma_f32_16x16x32_bf16 v[60:63], v[144:147], v[198:201], v[60:63]
	v_mfma_f32_16x16x32_bf16 v[60:63], v[140:143], v[194:197], v[60:63]
	v_mfma_f32_16x16x32_bf16 v[44:47], v[140:143], v[202:205], v[44:47]
	v_mfma_f32_16x16x32_bf16 v[44:47], v[144:147], v[206:209], v[44:47]
	v_mfma_f32_16x16x32_bf16 v[48:51], v[136:139], v[206:209], v[48:51]
	v_mfma_f32_16x16x32_bf16 v[48:51], v[132:135], v[202:205], v[48:51]
	v_mfma_f32_16x16x32_bf16 v[32:35], v[132:135], v[210:213], v[32:35]
	v_mfma_f32_16x16x32_bf16 v[32:35], v[136:139], v[214:217], v[32:35]
	v_mfma_f32_16x16x32_bf16 v[28:31], v[144:147], v[214:217], v[28:31]
	v_mfma_f32_16x16x32_bf16 v[28:31], v[140:143], v[210:213], v[28:31]
	v_mfma_f32_16x16x32_bf16 v[12:15], v[140:143], v[228:231], v[12:15]
	v_mfma_f32_16x16x32_bf16 v[12:15], v[144:147], v[232:235], v[12:15]
	v_mfma_f32_16x16x32_bf16 v[16:19], v[136:139], v[232:235], v[16:19]
	v_mfma_f32_16x16x32_bf16 v[16:19], v[132:135], v[228:231], v[16:19]
	v_mfma_f32_16x16x32_bf16 v[56:59], v[176:179], v[194:197], v[56:59]
	v_mfma_f32_16x16x32_bf16 v[56:59], v[182:185], v[198:201], v[56:59]
	v_mfma_f32_16x16x32_bf16 v[52:55], v[190:193], v[198:201], v[52:55]
	v_mfma_f32_16x16x32_bf16 v[52:55], v[186:189], v[194:197], v[52:55]
	v_mfma_f32_16x16x32_bf16 v[36:39], v[186:189], v[202:205], v[36:39]
	v_mfma_f32_16x16x32_bf16 v[36:39], v[190:193], v[206:209], v[36:39]
	v_mfma_f32_16x16x32_bf16 v[40:43], v[182:185], v[206:209], v[40:43]
	v_mfma_f32_16x16x32_bf16 v[40:43], v[176:179], v[202:205], v[40:43]
	v_mfma_f32_16x16x32_bf16 v[24:27], v[176:179], v[210:213], v[24:27]
	v_mfma_f32_16x16x32_bf16 v[24:27], v[182:185], v[214:217], v[24:27]
	v_mfma_f32_16x16x32_bf16 v[20:23], v[190:193], v[214:217], v[20:23]
	v_mfma_f32_16x16x32_bf16 v[20:23], v[186:189], v[210:213], v[20:23]
	v_mfma_f32_16x16x32_bf16 v[4:7], v[186:189], v[228:231], v[4:7]
	v_mfma_f32_16x16x32_bf16 v[4:7], v[190:193], v[232:235], v[4:7]
	v_mfma_f32_16x16x32_bf16 v[8:11], v[182:185], v[232:235], v[8:11]
	v_mfma_f32_16x16x32_bf16 v[8:11], v[176:179], v[228:231], v[8:11]
	s_setprio 0
	s_barrier
	s_add_i32 s52, 0, 0x18000
	s_add_i32 s53, 0, 0x1c000
	v_add_u32_e32 v144, s52, v155
	v_add_u32_e32 v180, s53, v155
	ds_read_b128 v[132:135], v144
	ds_read_b128 v[136:139], v144 offset:1024
	ds_read_b128 v[140:143], v144 offset:2048
	ds_read_b128 v[144:147], v144 offset:3072
	ds_read_b128 v[176:179], v180
	ds_read_b128 v[182:185], v180 offset:1024
	ds_read_b128 v[186:189], v180 offset:2048
	ds_read_b128 v[190:193], v180 offset:3072
	s_add_u32 s46, s46, 0x80000
	s_addc_u32 s47, s47, 0
	s_mov_b32 m0, s88
	ds_read_b128 v[194:197], v181 offset:32768
	ds_read_b128 v[198:201], v181 offset:33792
	ds_read_b128 v[202:205], v181 offset:34816
	ds_read_b128 v[206:209], v181 offset:35840
	ds_read_b128 v[210:213], v181 offset:36864
	ds_read_b128 v[214:217], v181 offset:37888
	ds_read_b128 v[228:231], v181 offset:38912
	ds_read_b128 v[232:235], v181 offset:39936
	global_load_lds_dwordx4 v152, s[46:47] sc0
	s_mov_b32 m0, s96
	s_nop 0
	global_load_lds_dwordx4 v148, s[46:47] sc0
	s_waitcnt vmcnt(8)
	s_waitcnt lgkmcnt(0)
	s_barrier
	s_setprio 1
	v_mfma_f32_16x16x32_bf16 v[128:131], v[132:135], v[194:197], v[128:131]
	v_mfma_f32_16x16x32_bf16 v[128:131], v[136:139], v[198:201], v[128:131]
	v_mfma_f32_16x16x32_bf16 v[124:127], v[144:147], v[198:201], v[124:127]
	v_mfma_f32_16x16x32_bf16 v[124:127], v[140:143], v[194:197], v[124:127]
	v_mfma_f32_16x16x32_bf16 v[108:111], v[140:143], v[202:205], v[108:111]
	v_mfma_f32_16x16x32_bf16 v[108:111], v[144:147], v[206:209], v[108:111]
	v_mfma_f32_16x16x32_bf16 v[112:115], v[136:139], v[206:209], v[112:115]
	v_mfma_f32_16x16x32_bf16 v[112:115], v[132:135], v[202:205], v[112:115]
	v_mfma_f32_16x16x32_bf16 v[96:99], v[132:135], v[210:213], v[96:99]
	v_mfma_f32_16x16x32_bf16 v[96:99], v[136:139], v[214:217], v[96:99]
	v_mfma_f32_16x16x32_bf16 v[92:95], v[144:147], v[214:217], v[92:95]
	v_mfma_f32_16x16x32_bf16 v[92:95], v[140:143], v[210:213], v[92:95]
	v_mfma_f32_16x16x32_bf16 v[76:79], v[140:143], v[228:231], v[76:79]
	v_mfma_f32_16x16x32_bf16 v[76:79], v[144:147], v[232:235], v[76:79]
	v_mfma_f32_16x16x32_bf16 v[80:83], v[136:139], v[232:235], v[80:83]
	v_mfma_f32_16x16x32_bf16 v[80:83], v[132:135], v[228:231], v[80:83]
	v_mfma_f32_16x16x32_bf16 v[120:123], v[176:179], v[194:197], v[120:123]
	v_mfma_f32_16x16x32_bf16 v[120:123], v[182:185], v[198:201], v[120:123]
	v_mfma_f32_16x16x32_bf16 v[116:119], v[190:193], v[198:201], v[116:119]
	v_mfma_f32_16x16x32_bf16 v[116:119], v[186:189], v[194:197], v[116:119]
	v_mfma_f32_16x16x32_bf16 v[100:103], v[186:189], v[202:205], v[100:103]
	v_mfma_f32_16x16x32_bf16 v[100:103], v[190:193], v[206:209], v[100:103]
	v_mfma_f32_16x16x32_bf16 v[104:107], v[182:185], v[206:209], v[104:107]
	v_mfma_f32_16x16x32_bf16 v[104:107], v[176:179], v[202:205], v[104:107]
	v_mfma_f32_16x16x32_bf16 v[88:91], v[176:179], v[210:213], v[88:91]
	v_mfma_f32_16x16x32_bf16 v[88:91], v[182:185], v[214:217], v[88:91]
	v_mfma_f32_16x16x32_bf16 v[84:87], v[190:193], v[214:217], v[84:87]
	v_mfma_f32_16x16x32_bf16 v[84:87], v[186:189], v[210:213], v[84:87]
	v_mfma_f32_16x16x32_bf16 v[68:71], v[186:189], v[228:231], v[68:71]
	v_mfma_f32_16x16x32_bf16 v[68:71], v[190:193], v[232:235], v[68:71]
	v_mfma_f32_16x16x32_bf16 v[72:75], v[182:185], v[232:235], v[72:75]
	v_mfma_f32_16x16x32_bf16 v[72:75], v[176:179], v[228:231], v[72:75]
	s_setprio 0
	s_barrier
	s_add_u32 s46, s34, 0x70000
	s_addc_u32 s47, s35, 0
	s_add_i32 s52, s52, s2
	s_mov_b32 m0, s52
	ds_read_b128 v[194:197], v181 offset:49152
	ds_read_b128 v[198:201], v181 offset:50176
	ds_read_b128 v[202:205], v181 offset:51200
	ds_read_b128 v[206:209], v181 offset:52224
	ds_read_b128 v[210:213], v181 offset:53248
	ds_read_b128 v[214:217], v181 offset:54272
	ds_read_b128 v[228:231], v181 offset:55296
	ds_read_b128 v[232:235], v181 offset:56320
	global_load_lds_dwordx4 v150, s[46:47] sc0
	s_add_i32 m0, s52, 0x2000
	s_add_u32 s34, s34, 0x74000
	global_load_lds_dwordx4 v0, s[46:47] sc0
	s_addc_u32 s35, s35, 0
	s_add_i32 s46, s53, s2
	s_mov_b32 m0, s46
	s_nop 0
	global_load_lds_dwordx4 v150, s[34:35] sc0
	s_add_i32 m0, s46, 0x2000
	s_nop 0
	global_load_lds_dwordx4 v0, s[34:35] sc0
	s_mov_b32 m0, s97
	s_nop 0
	global_load_lds_dwordx4 v152, s[100:101] sc0
	s_mov_b32 m0, s76
	s_nop 0
	global_load_lds_dwordx4 v148, s[100:101] sc0
	s_waitcnt vmcnt(8)
	s_waitcnt lgkmcnt(0)
	s_barrier
	s_setprio 1
	v_mfma_f32_16x16x32_bf16 v[64:67], v[132:135], v[194:197], v[64:67]
	v_mfma_f32_16x16x32_bf16 v[64:67], v[136:139], v[198:201], v[64:67]
	v_mfma_f32_16x16x32_bf16 v[60:63], v[144:147], v[198:201], v[60:63]
	v_mfma_f32_16x16x32_bf16 v[60:63], v[140:143], v[194:197], v[60:63]
	v_mfma_f32_16x16x32_bf16 v[44:47], v[140:143], v[202:205], v[44:47]
	v_mfma_f32_16x16x32_bf16 v[44:47], v[144:147], v[206:209], v[44:47]
	v_mfma_f32_16x16x32_bf16 v[48:51], v[136:139], v[206:209], v[48:51]
	v_mfma_f32_16x16x32_bf16 v[48:51], v[132:135], v[202:205], v[48:51]
	v_mfma_f32_16x16x32_bf16 v[32:35], v[132:135], v[210:213], v[32:35]
	v_mfma_f32_16x16x32_bf16 v[32:35], v[136:139], v[214:217], v[32:35]
	v_mfma_f32_16x16x32_bf16 v[28:31], v[144:147], v[214:217], v[28:31]
	v_mfma_f32_16x16x32_bf16 v[28:31], v[140:143], v[210:213], v[28:31]
	v_mfma_f32_16x16x32_bf16 v[12:15], v[140:143], v[228:231], v[12:15]
	v_mfma_f32_16x16x32_bf16 v[12:15], v[144:147], v[232:235], v[12:15]
	v_mfma_f32_16x16x32_bf16 v[16:19], v[136:139], v[232:235], v[16:19]
	v_mfma_f32_16x16x32_bf16 v[16:19], v[132:135], v[228:231], v[16:19]
	v_mfma_f32_16x16x32_bf16 v[56:59], v[176:179], v[194:197], v[56:59]
	v_mfma_f32_16x16x32_bf16 v[56:59], v[182:185], v[198:201], v[56:59]
	v_mfma_f32_16x16x32_bf16 v[52:55], v[190:193], v[198:201], v[52:55]
	v_mfma_f32_16x16x32_bf16 v[52:55], v[186:189], v[194:197], v[52:55]
	v_mfma_f32_16x16x32_bf16 v[36:39], v[186:189], v[202:205], v[36:39]
	v_mfma_f32_16x16x32_bf16 v[36:39], v[190:193], v[206:209], v[36:39]
	v_mfma_f32_16x16x32_bf16 v[40:43], v[182:185], v[206:209], v[40:43]
	v_mfma_f32_16x16x32_bf16 v[40:43], v[176:179], v[202:205], v[40:43]
	v_mfma_f32_16x16x32_bf16 v[24:27], v[176:179], v[210:213], v[24:27]
	v_mfma_f32_16x16x32_bf16 v[24:27], v[182:185], v[214:217], v[24:27]
	v_mfma_f32_16x16x32_bf16 v[20:23], v[190:193], v[214:217], v[20:23]
	v_mfma_f32_16x16x32_bf16 v[20:23], v[186:189], v[210:213], v[20:23]
	v_mfma_f32_16x16x32_bf16 v[4:7], v[186:189], v[228:231], v[4:7]
	v_mfma_f32_16x16x32_bf16 v[4:7], v[190:193], v[232:235], v[4:7]
	v_mfma_f32_16x16x32_bf16 v[8:11], v[182:185], v[232:235], v[8:11]
	v_mfma_f32_16x16x32_bf16 v[8:11], v[176:179], v[228:231], v[8:11]
	s_setprio 0
	s_barrier
	s_add_i32 vcc_hi, vcc_hi, 2
	s_add_u32 s63, s63, 0xe0000
	s_addc_u32 vcc_lo, vcc_lo, 0
	s_add_u32 s44, s44, 0x100
	s_addc_u32 s45, s45, 0
	s_cmp_gt_u32 vcc_hi, 29
	s_cbranch_scc0 .LBB0_243
	s_and_b64 vcc, exec, s[28:29]
	s_cbranch_vccz .LBB0_246
	s_barrier

.LBB0_544:
	v_readlane_b32 s26, v241, 48
	v_mov_b32_e32 v14, v156
	v_readlane_b32 s27, v241, 49
	s_add_i32 s70, s70, 1
	s_andn2_b64 vcc, exec, s[26:27]
	v_readfirstlane_b32 s36, v14
	s_cbranch_vccnz .LBB0_582
	v_lshlrev_b32_e32 v1, 4, v14
	v_add_u32_e32 v0, 0x2000, v1
	v_ashrrev_i32_e32 v3, 31, v0
	v_lshrrev_b32_e32 v3, 22, v3
	v_add_u32_e32 v3, v0, v3
	v_ashrrev_i32_e32 v3, 10, v3
	v_mul_i32_i24_e32 v4, 0x400, v3
	v_sub_u32_e32 v0, v0, v4
	v_lshrrev_b32_e32 v4, 4, v0
	v_bitop3_b32 v0, v4, v0, 32 bitop3:0x6c
	v_ashrrev_i32_e32 v4, 31, v0
	v_lshrrev_b32_e32 v4, 26, v4
	v_add_u32_e32 v4, v0, v4
	v_lshlrev_b32_e32 v6, 3, v3
	v_ashrrev_i32_e32 v5, 6, v4
	v_and_b32_e32 v6, -16, v6
	s_add_u32 s2, s88, s28
	v_readlane_b32 s1, v240, 13
	v_add_u32_e32 v6, v5, v6
	s_addc_u32 s19, s1, s29
	v_and_b32_e32 v5, 3, v5
	s_mov_b32 s1, 0x1ffffe0
	v_lshrrev_b32_e32 v7, 2, v6
	v_lshlrev_b32_e32 v8, 1, v6
	v_and_or_b32 v5, v6, s1, v5
	v_and_b32_e32 v7, 4, v7
	v_and_b32_e32 v8, 24, v8
	v_lshlrev_b32_e32 v3, 5, v3
	v_or3_b32 v5, v5, v7, v8
	v_and_b32_e32 v8, 32, v3
	v_and_b32_e32 v3, 0xc0, v4
	v_sub_u32_e32 v0, v0, v3
	v_ashrrev_i16_sdwa v0, v220, sext(v0) dst_sel:DWORD dst_unused:UNUSED_PAD src0_sel:DWORD src1_sel:BYTE_0
	v_bfe_i32 v9, v0, 0, 16
	v_add_u32_e32 v3, v8, v9
	v_mul_lo_u32 v10, v6, s37
	v_lshlrev_b32_e32 v0, 1, v3
	v_add_lshl_u32 v172, v3, v10, 1
	v_bfe_i32 v3, v14, 27, 1
	v_lshrrev_b32_e32 v3, 22, v3
	v_add_u32_e32 v3, v1, v3
	v_and_b32_e32 v3, 0xfffffc00, v3
	v_sub_u32_e32 v1, v1, v3
	v_lshl_add_u32 v0, v5, 7, v0
	v_lshrrev_b32_e32 v3, 4, v1
	v_ashrrev_i32_e32 v5, 31, v14
	v_bitop3_b32 v1, v3, v1, 32 bitop3:0x6c
	v_lshrrev_b32_e32 v5, 26, v5
	v_ashrrev_i32_e32 v3, 31, v1
	v_add_u32_e32 v5, v14, v5
	v_lshrrev_b32_e32 v3, 26, v3
	v_ashrrev_i32_e32 v5, 6, v5
	v_add_u32_e32 v3, v1, v3
	v_lshlrev_b32_e32 v6, 3, v5
	v_ashrrev_i32_e32 v4, 6, v3
	v_and_b32_e32 v6, -16, v6
	v_add_u32_e32 v6, v4, v6
	v_and_b32_e32 v3, 0xc0, v3
	v_and_b32_e32 v4, 3, v4
	v_lshrrev_b32_e32 v7, 2, v6
	v_lshlrev_b32_e32 v11, 1, v6
	v_sub_u32_e32 v1, v1, v3
	s_ashr_i32 s39, s36, 6
	v_and_or_b32 v4, v6, s1, v4
	v_and_b32_e32 v7, 4, v7
	v_and_b32_e32 v11, 24, v11
	v_lshlrev_b32_e32 v5, 5, v5
	v_ashrrev_i16_sdwa v1, v220, sext(v1) dst_sel:DWORD dst_unused:UNUSED_PAD src0_sel:DWORD src1_sel:BYTE_0
	s_ashr_i32 s38, s36, 8
	s_lshl_b32 s26, s37, 8
	s_lshl_b32 s33, s37, 9
	s_lshl_b32 s58, s39, 10
	v_or3_b32 v4, v4, v7, v11
	v_and_b32_e32 v11, 32, v5
	v_bfe_i32 v12, v1, 0, 16
	v_readlane_b32 s28, v241, 58
	v_add_u32_e32 v1, v11, v12
	v_readlane_b32 s29, v241, 59
	s_add_u32 s34, s2, s28
	v_lshlrev_b32_e32 v3, 1, v1
	s_addc_u32 s35, s19, s29
	s_add_i32 s59, s58, 0
	v_lshl_add_u32 v174, v4, 7, v3
	s_add_i32 m0, s59, 0x10000
	v_readlane_b32 s27, v241, 53
	global_load_lds_dwordx4 v174, s[34:35] sc0
	s_add_i32 m0, s59, 0x12000
	s_add_u32 s28, s34, 0x4000
	global_load_lds_dwordx4 v0, s[34:35] sc0
	s_addc_u32 s29, s35, 0
	s_add_i32 m0, s59, 0x14000
	s_mul_hi_i32 s1, s33, s27
	s_mul_i32 s27, s33, s27
	global_load_lds_dwordx4 v174, s[28:29] sc0
	s_add_i32 m0, s59, 0x16000
	s_add_u32 s56, s22, s27
	v_mul_lo_u32 v13, v6, s37
	s_addc_u32 s57, s23, s1
	s_add_i32 s60, s59, 0x2000
	v_add_lshl_u32 v176, v1, v13, 1
	global_load_lds_dwordx4 v0, s[28:29] sc0
	s_mov_b32 m0, s59
	s_add_u32 s28, s56, s26
	global_load_lds_dwordx4 v176, s[56:57] sc0
	s_mov_b32 m0, s60
	s_addc_u32 s29, s57, 0
	s_add_i32 s61, s59, 0x4000
	global_load_lds_dwordx4 v172, s[56:57] sc0
	s_mov_b32 m0, s61
	s_add_i32 s62, s59, 0x6000
	global_load_lds_dwordx4 v176, s[28:29] sc0
	s_mov_b32 m0, s62
	v_mov_b32_e32 v177, v2
	global_load_lds_dwordx4 v172, s[28:29] sc0
	v_mov_b32_e32 v173, v2
	s_cmp_eq_u32 s38, 1
	s_mov_b32 s27, s65
	v_lshl_add_u64 v[4:5], s[56:57], 0, v[176:177]
	s_cselect_b64 s[28:29], -1, 0
	s_cmp_lg_u32 s38, 1
	v_lshl_add_u64 v[6:7], s[56:57], 0, v[172:173]
	s_cbranch_scc1 .LBB0_547
	s_barrier

.LBB0_559:
	s_add_i32 vcc_lo, s34, 2
	s_add_u32 s35, s42, 0x80
	s_addc_u32 s52, s43, 0
	s_add_i32 s53, 0, 0x10000
	s_cmp_eq_u32 s77, s34
	s_cselect_b32 s57, s51, s52
	s_cselect_b32 s56, s50, s35
	s_cselect_b32 s35, s36, s97
	s_cselect_b32 s34, s37, s49
	s_add_i32 s68, 0, 0x14000
	v_add_u32_e32 v136, s53, v200
	v_add_u32_e32 v186, s68, v200
	ds_read_b128 v[116:119], v136
	ds_read_b128 v[120:123], v136 offset:1024
	ds_read_b128 v[124:127], v136 offset:2048
	ds_read_b128 v[136:139], v136 offset:3072
	ds_read_b128 v[148:151], v186
	ds_read_b128 v[152:155], v186 offset:1024
	ds_read_b128 v[182:185], v186 offset:2048
	ds_read_b128 v[186:189], v186 offset:3072
	s_add_i32 m0, s59, 0xc000
	ds_read_b128 v[190:193], v202
	ds_read_b128 v[194:197], v202 offset:1024
	ds_read_b128 v[204:207], v202 offset:2048
	ds_read_b128 v[208:211], v202 offset:3072
	ds_read_b128 v[212:215], v202 offset:4096
	ds_read_b128 v[216:219], v202 offset:5120
	ds_read_b128 v[228:231], v202 offset:6144
	ds_read_b128 v[232:235], v202 offset:7168
	global_load_lds_dwordx4 v178, s[42:43] sc0
	s_add_i32 m0, s59, 0xe000
	s_nop 0
	global_load_lds_dwordx4 v180, s[42:43] sc0
	s_waitcnt vmcnt(8)
	s_waitcnt lgkmcnt(0)
	s_barrier
	s_setprio 1
	v_mfma_f32_16x16x32_bf16 v[144:147], v[116:119], v[190:193], v[144:147]
	v_mfma_f32_16x16x32_bf16 v[144:147], v[120:123], v[194:197], v[144:147]
	v_mfma_f32_16x16x32_bf16 v[140:143], v[136:139], v[194:197], v[140:143]
	v_mfma_f32_16x16x32_bf16 v[140:143], v[124:127], v[190:193], v[140:143]
	v_mfma_f32_16x16x32_bf16 v[108:111], v[124:127], v[204:207], v[108:111]
	v_mfma_f32_16x16x32_bf16 v[108:111], v[136:139], v[208:211], v[108:111]
	v_mfma_f32_16x16x32_bf16 v[112:115], v[120:123], v[208:211], v[112:115]
	v_mfma_f32_16x16x32_bf16 v[112:115], v[116:119], v[204:207], v[112:115]
	v_mfma_f32_16x16x32_bf16 v[96:99], v[116:119], v[212:215], v[96:99]
	v_mfma_f32_16x16x32_bf16 v[96:99], v[120:123], v[216:219], v[96:99]
	v_mfma_f32_16x16x32_bf16 v[92:95], v[136:139], v[216:219], v[92:95]
	v_mfma_f32_16x16x32_bf16 v[92:95], v[124:127], v[212:215], v[92:95]
	v_mfma_f32_16x16x32_bf16 v[76:79], v[124:127], v[228:231], v[76:79]
	v_mfma_f32_16x16x32_bf16 v[76:79], v[136:139], v[232:235], v[76:79]
	v_mfma_f32_16x16x32_bf16 v[80:83], v[120:123], v[232:235], v[80:83]
	v_mfma_f32_16x16x32_bf16 v[80:83], v[116:119], v[228:231], v[80:83]
	v_mfma_f32_16x16x32_bf16 v[132:135], v[148:151], v[190:193], v[132:135]
	v_mfma_f32_16x16x32_bf16 v[132:135], v[152:155], v[194:197], v[132:135]
	v_mfma_f32_16x16x32_bf16 v[128:131], v[186:189], v[194:197], v[128:131]
	v_mfma_f32_16x16x32_bf16 v[128:131], v[182:185], v[190:193], v[128:131]
	v_mfma_f32_16x16x32_bf16 v[100:103], v[182:185], v[204:207], v[100:103]
	v_mfma_f32_16x16x32_bf16 v[100:103], v[186:189], v[208:211], v[100:103]
	v_mfma_f32_16x16x32_bf16 v[104:107], v[152:155], v[208:211], v[104:107]
	v_mfma_f32_16x16x32_bf16 v[104:107], v[148:151], v[204:207], v[104:107]
	v_mfma_f32_16x16x32_bf16 v[88:91], v[148:151], v[212:215], v[88:91]
	v_mfma_f32_16x16x32_bf16 v[88:91], v[152:155], v[216:219], v[88:91]
	v_mfma_f32_16x16x32_bf16 v[84:87], v[186:189], v[216:219], v[84:87]
	v_mfma_f32_16x16x32_bf16 v[84:87], v[182:185], v[212:215], v[84:87]
	v_mfma_f32_16x16x32_bf16 v[68:71], v[182:185], v[228:231], v[68:71]
	v_mfma_f32_16x16x32_bf16 v[68:71], v[186:189], v[232:235], v[68:71]
	v_mfma_f32_16x16x32_bf16 v[72:75], v[152:155], v[232:235], v[72:75]
	v_mfma_f32_16x16x32_bf16 v[72:75], v[148:151], v[228:231], v[72:75]
	s_setprio 0
	s_barrier
	s_add_u32 s100, s56, s14
	s_addc_u32 s101, s57, s15
	s_add_i32 s52, s53, s58
	s_mov_b32 m0, s52
	ds_read_b128 v[190:193], v202 offset:16384
	ds_read_b128 v[194:197], v202 offset:17408
	ds_read_b128 v[204:207], v202 offset:18432
	ds_read_b128 v[208:211], v202 offset:19456
	ds_read_b128 v[212:215], v202 offset:20480
	ds_read_b128 v[216:219], v202 offset:21504
	ds_read_b128 v[228:231], v202 offset:22528
	ds_read_b128 v[232:235], v202 offset:23552
	global_load_lds_dwordx4 v174, s[34:35] sc0
	s_add_i32 m0, s52, 0x2000
	s_add_u32 s52, s34, 0x4000
	s_addc_u32 s53, s35, 0
	s_add_i32 s68, s68, s58
	global_load_lds_dwordx4 v0, s[34:35] sc0
	s_mov_b32 m0, s68
	s_nop 0
	global_load_lds_dwordx4 v174, s[52:53] sc0
	s_add_i32 m0, s68, 0x2000
	s_nop 0
	global_load_lds_dwordx4 v0, s[52:53] sc0
	s_mov_b32 m0, s59
	s_nop 0
	global_load_lds_dwordx4 v176, s[56:57] sc0
	s_mov_b32 m0, s60
	s_nop 0
	global_load_lds_dwordx4 v172, s[56:57] sc0
	s_waitcnt vmcnt(8)
	s_waitcnt lgkmcnt(0)
	s_barrier
	s_setprio 1
	v_mfma_f32_16x16x32_bf16 v[64:67], v[116:119], v[190:193], v[64:67]
	v_mfma_f32_16x16x32_bf16 v[64:67], v[120:123], v[194:197], v[64:67]
	v_mfma_f32_16x16x32_bf16 v[60:63], v[136:139], v[194:197], v[60:63]
	v_mfma_f32_16x16x32_bf16 v[60:63], v[124:127], v[190:193], v[60:63]
	v_mfma_f32_16x16x32_bf16 v[44:47], v[124:127], v[204:207], v[44:47]
	v_mfma_f32_16x16x32_bf16 v[44:47], v[136:139], v[208:211], v[44:47]
	v_mfma_f32_16x16x32_bf16 v[48:51], v[120:123], v[208:211], v[48:51]
	v_mfma_f32_16x16x32_bf16 v[48:51], v[116:119], v[204:207], v[48:51]
	v_mfma_f32_16x16x32_bf16 v[32:35], v[116:119], v[212:215], v[32:35]
	v_mfma_f32_16x16x32_bf16 v[32:35], v[120:123], v[216:219], v[32:35]
	v_mfma_f32_16x16x32_bf16 v[28:31], v[136:139], v[216:219], v[28:31]
	v_mfma_f32_16x16x32_bf16 v[28:31], v[124:127], v[212:215], v[28:31]
	v_mfma_f32_16x16x32_bf16 v[12:15], v[124:127], v[228:231], v[12:15]
	v_mfma_f32_16x16x32_bf16 v[12:15], v[136:139], v[232:235], v[12:15]
	v_mfma_f32_16x16x32_bf16 v[16:19], v[120:123], v[232:235], v[16:19]
	v_mfma_f32_16x16x32_bf16 v[16:19], v[116:119], v[228:231], v[16:19]
	v_mfma_f32_16x16x32_bf16 v[56:59], v[148:151], v[190:193], v[56:59]
	v_mfma_f32_16x16x32_bf16 v[56:59], v[152:155], v[194:197], v[56:59]
	v_mfma_f32_16x16x32_bf16 v[52:55], v[186:189], v[194:197], v[52:55]
	v_mfma_f32_16x16x32_bf16 v[52:55], v[182:185], v[190:193], v[52:55]
	v_mfma_f32_16x16x32_bf16 v[36:39], v[182:185], v[204:207], v[36:39]
	v_mfma_f32_16x16x32_bf16 v[36:39], v[186:189], v[208:211], v[36:39]
	v_mfma_f32_16x16x32_bf16 v[40:43], v[152:155], v[208:211], v[40:43]
	v_mfma_f32_16x16x32_bf16 v[40:43], v[148:151], v[204:207], v[40:43]
	v_mfma_f32_16x16x32_bf16 v[24:27], v[148:151], v[212:215], v[24:27]
	v_mfma_f32_16x16x32_bf16 v[24:27], v[152:155], v[216:219], v[24:27]
	v_mfma_f32_16x16x32_bf16 v[20:23], v[186:189], v[216:219], v[20:23]
	v_mfma_f32_16x16x32_bf16 v[20:23], v[182:185], v[212:215], v[20:23]
	v_mfma_f32_16x16x32_bf16 v[4:7], v[182:185], v[228:231], v[4:7]
	v_mfma_f32_16x16x32_bf16 v[4:7], v[186:189], v[232:235], v[4:7]
	v_mfma_f32_16x16x32_bf16 v[8:11], v[152:155], v[232:235], v[8:11]
	v_mfma_f32_16x16x32_bf16 v[8:11], v[148:151], v[228:231], v[8:11]
	s_setprio 0
	s_barrier
	s_add_i32 s68, 0, 0x18000
	s_add_i32 vcc_hi, 0, 0x1c000
	v_add_u32_e32 v136, s68, v200
	v_add_u32_e32 v186, vcc_hi, v200
	ds_read_b128 v[116:119], v136
	ds_read_b128 v[120:123], v136 offset:1024
	ds_read_b128 v[124:127], v136 offset:2048
	ds_read_b128 v[136:139], v136 offset:3072
	ds_read_b128 v[148:151], v186
	ds_read_b128 v[152:155], v186 offset:1024
	ds_read_b128 v[182:185], v186 offset:2048
	ds_read_b128 v[186:189], v186 offset:3072
	s_add_u32 s52, s56, s26
	s_addc_u32 s53, s57, 0
	s_mov_b32 m0, s61
	ds_read_b128 v[190:193], v202 offset:32768
	ds_read_b128 v[194:197], v202 offset:33792
	ds_read_b128 v[204:207], v202 offset:34816
	ds_read_b128 v[208:211], v202 offset:35840
	ds_read_b128 v[212:215], v202 offset:36864
	ds_read_b128 v[216:219], v202 offset:37888
	ds_read_b128 v[228:231], v202 offset:38912
	ds_read_b128 v[232:235], v202 offset:39936
	global_load_lds_dwordx4 v176, s[52:53] sc0
	s_mov_b32 m0, s62
	s_nop 0
	global_load_lds_dwordx4 v172, s[52:53] sc0
	s_waitcnt vmcnt(8)
	s_waitcnt lgkmcnt(0)
	s_barrier
	s_setprio 1
	v_mfma_f32_16x16x32_bf16 v[144:147], v[116:119], v[190:193], v[144:147]
	v_mfma_f32_16x16x32_bf16 v[144:147], v[120:123], v[194:197], v[144:147]
	v_mfma_f32_16x16x32_bf16 v[140:143], v[136:139], v[194:197], v[140:143]
	v_mfma_f32_16x16x32_bf16 v[140:143], v[124:127], v[190:193], v[140:143]
	v_mfma_f32_16x16x32_bf16 v[108:111], v[124:127], v[204:207], v[108:111]
	v_mfma_f32_16x16x32_bf16 v[108:111], v[136:139], v[208:211], v[108:111]
	v_mfma_f32_16x16x32_bf16 v[112:115], v[120:123], v[208:211], v[112:115]
	v_mfma_f32_16x16x32_bf16 v[112:115], v[116:119], v[204:207], v[112:115]
	v_mfma_f32_16x16x32_bf16 v[96:99], v[116:119], v[212:215], v[96:99]
	v_mfma_f32_16x16x32_bf16 v[96:99], v[120:123], v[216:219], v[96:99]
	v_mfma_f32_16x16x32_bf16 v[92:95], v[136:139], v[216:219], v[92:95]
	v_mfma_f32_16x16x32_bf16 v[92:95], v[124:127], v[212:215], v[92:95]
	v_mfma_f32_16x16x32_bf16 v[76:79], v[124:127], v[228:231], v[76:79]
	v_mfma_f32_16x16x32_bf16 v[76:79], v[136:139], v[232:235], v[76:79]
	v_mfma_f32_16x16x32_bf16 v[80:83], v[120:123], v[232:235], v[80:83]
	v_mfma_f32_16x16x32_bf16 v[80:83], v[116:119], v[228:231], v[80:83]
	v_mfma_f32_16x16x32_bf16 v[132:135], v[148:151], v[190:193], v[132:135]
	v_mfma_f32_16x16x32_bf16 v[132:135], v[152:155], v[194:197], v[132:135]
	v_mfma_f32_16x16x32_bf16 v[128:131], v[186:189], v[194:197], v[128:131]
	v_mfma_f32_16x16x32_bf16 v[128:131], v[182:185], v[190:193], v[128:131]
	v_mfma_f32_16x16x32_bf16 v[100:103], v[182:185], v[204:207], v[100:103]
	v_mfma_f32_16x16x32_bf16 v[100:103], v[186:189], v[208:211], v[100:103]
	v_mfma_f32_16x16x32_bf16 v[104:107], v[152:155], v[208:211], v[104:107]
	v_mfma_f32_16x16x32_bf16 v[104:107], v[148:151], v[204:207], v[104:107]
	v_mfma_f32_16x16x32_bf16 v[88:91], v[148:151], v[212:215], v[88:91]
	v_mfma_f32_16x16x32_bf16 v[88:91], v[152:155], v[216:219], v[88:91]
	v_mfma_f32_16x16x32_bf16 v[84:87], v[186:189], v[216:219], v[84:87]
	v_mfma_f32_16x16x32_bf16 v[84:87], v[182:185], v[212:215], v[84:87]
	v_mfma_f32_16x16x32_bf16 v[68:71], v[182:185], v[228:231], v[68:71]
	v_mfma_f32_16x16x32_bf16 v[68:71], v[186:189], v[232:235], v[68:71]
	v_mfma_f32_16x16x32_bf16 v[72:75], v[152:155], v[232:235], v[72:75]
	v_mfma_f32_16x16x32_bf16 v[72:75], v[148:151], v[228:231], v[72:75]
	s_setprio 0
	s_barrier
	s_add_u32 s52, s34, 0x40000
	s_addc_u32 s53, s35, 0
	s_add_i32 s56, s68, s58
	s_mov_b32 m0, s56
	ds_read_b128 v[190:193], v202 offset:49152
	ds_read_b128 v[194:197], v202 offset:50176
	ds_read_b128 v[204:207], v202 offset:51200
	ds_read_b128 v[208:211], v202 offset:52224
	ds_read_b128 v[212:215], v202 offset:53248
	ds_read_b128 v[216:219], v202 offset:54272
	ds_read_b128 v[228:231], v202 offset:55296
	ds_read_b128 v[232:235], v202 offset:56320
	global_load_lds_dwordx4 v174, s[52:53] sc0
	s_add_i32 m0, s56, 0x2000
	s_add_u32 s34, s34, 0x44000
	global_load_lds_dwordx4 v0, s[52:53] sc0
	s_addc_u32 s35, s35, 0
	s_add_i32 s52, vcc_hi, s58
	s_mov_b32 m0, s52
	s_nop 0
	global_load_lds_dwordx4 v174, s[34:35] sc0
	s_add_i32 m0, s52, 0x2000
	s_nop 0
	global_load_lds_dwordx4 v0, s[34:35] sc0
	s_mov_b32 m0, s71
	s_nop 0
	global_load_lds_dwordx4 v176, s[100:101] sc0
	s_mov_b32 m0, s76
	s_nop 0
	global_load_lds_dwordx4 v172, s[100:101] sc0
	s_waitcnt vmcnt(8)
	s_waitcnt lgkmcnt(0)
	s_barrier
	s_setprio 1
	v_mfma_f32_16x16x32_bf16 v[64:67], v[116:119], v[190:193], v[64:67]
	v_mfma_f32_16x16x32_bf16 v[64:67], v[120:123], v[194:197], v[64:67]
	v_mfma_f32_16x16x32_bf16 v[60:63], v[136:139], v[194:197], v[60:63]
	v_mfma_f32_16x16x32_bf16 v[60:63], v[124:127], v[190:193], v[60:63]
	v_mfma_f32_16x16x32_bf16 v[44:47], v[124:127], v[204:207], v[44:47]
	v_mfma_f32_16x16x32_bf16 v[44:47], v[136:139], v[208:211], v[44:47]
	v_mfma_f32_16x16x32_bf16 v[48:51], v[120:123], v[208:211], v[48:51]
	v_mfma_f32_16x16x32_bf16 v[48:51], v[116:119], v[204:207], v[48:51]
	v_mfma_f32_16x16x32_bf16 v[32:35], v[116:119], v[212:215], v[32:35]
	v_mfma_f32_16x16x32_bf16 v[32:35], v[120:123], v[216:219], v[32:35]
	v_mfma_f32_16x16x32_bf16 v[28:31], v[136:139], v[216:219], v[28:31]
	v_mfma_f32_16x16x32_bf16 v[28:31], v[124:127], v[212:215], v[28:31]
	v_mfma_f32_16x16x32_bf16 v[12:15], v[124:127], v[228:231], v[12:15]
	v_mfma_f32_16x16x32_bf16 v[12:15], v[136:139], v[232:235], v[12:15]
	v_mfma_f32_16x16x32_bf16 v[16:19], v[120:123], v[232:235], v[16:19]
	v_mfma_f32_16x16x32_bf16 v[16:19], v[116:119], v[228:231], v[16:19]
	v_mfma_f32_16x16x32_bf16 v[56:59], v[148:151], v[190:193], v[56:59]
	v_mfma_f32_16x16x32_bf16 v[56:59], v[152:155], v[194:197], v[56:59]
	v_mfma_f32_16x16x32_bf16 v[52:55], v[186:189], v[194:197], v[52:55]
	v_mfma_f32_16x16x32_bf16 v[52:55], v[182:185], v[190:193], v[52:55]
	v_mfma_f32_16x16x32_bf16 v[36:39], v[182:185], v[204:207], v[36:39]
	v_mfma_f32_16x16x32_bf16 v[36:39], v[186:189], v[208:211], v[36:39]
	v_mfma_f32_16x16x32_bf16 v[40:43], v[152:155], v[208:211], v[40:43]
	v_mfma_f32_16x16x32_bf16 v[40:43], v[148:151], v[204:207], v[40:43]
	v_mfma_f32_16x16x32_bf16 v[24:27], v[148:151], v[212:215], v[24:27]
	v_mfma_f32_16x16x32_bf16 v[24:27], v[152:155], v[216:219], v[24:27]
	v_mfma_f32_16x16x32_bf16 v[20:23], v[186:189], v[216:219], v[20:23]
	v_mfma_f32_16x16x32_bf16 v[20:23], v[182:185], v[212:215], v[20:23]
	v_mfma_f32_16x16x32_bf16 v[4:7], v[182:185], v[228:231], v[4:7]
	v_mfma_f32_16x16x32_bf16 v[4:7], v[186:189], v[232:235], v[4:7]
	v_mfma_f32_16x16x32_bf16 v[8:11], v[152:155], v[232:235], v[8:11]
	v_mfma_f32_16x16x32_bf16 v[8:11], v[148:151], v[228:231], v[8:11]
	s_setprio 0
	s_barrier
	s_add_u32 s49, s49, 0x80000
	s_addc_u32 s97, s97, 0
	s_add_u32 s42, s42, 0x100
	s_addc_u32 s43, s43, 0
	s_cmp_ge_u32 vcc_lo, s69
	s_mov_b32 s34, vcc_lo
	s_cbranch_scc0 .LBB0_559
	s_and_b64 vcc, exec, s[46:47]
	s_cbranch_vccz .LBB0_562
	s_barrier
